# st2 SSD inter-chunk state carry re-issued as four double-buffered 16-chunk batches (8 serial load round trips overlapped)
# speedup vs baseline: 1.0018x; 1.0018x over previous
.LBB0_815:
	s_andn2_b64 vcc, exec, s[2:3]
	s_cbranch_vccnz .LBB0_817
	v_lshl_add_u32 v0, s45, 8, v2
	v_ashrrev_i32_e32 v4, 14, v0
	v_bfe_u32 v5, v0, 12, 2
	v_and_b32_e32 v6, 0xfff, v0
	v_lshlrev_b32_e32 v7, 20, v4
	v_lshl_or_b32 v7, v5, 12, v7
	v_add_u32_e32 v7, v7, v6
	v_lshlrev_b32_e32 v176, 2, v7
	v_lshlrev_b32_e32 v180, 1, v7
	v_lshlrev_b32_e32 v7, 8, v4
	v_lshl_or_b32 v7, v5, 6, v7
	v_lshlrev_b32_e32 v144, 2, v7
	s_add_u32 s4, s82, 0x69f0000
	s_addc_u32 s5, s83, 0
	s_add_u32 s0, s82, 0xfbb9000
	s_addc_u32 s1, s83, 0
	s_add_u32 s2, s82, 0x103b9000
	s_addc_u32 s3, s83, 0
	global_store_short v180, v169, s[2:3]
	s_add_u32 s2, s2, 0x8000
	s_addc_u32 s3, s3, 0
	global_load_dwordx4 v[0:3], v144, s[4:5] offset:0
	global_load_dwordx4 v[4:7], v144, s[4:5] offset:16
	global_load_dwordx4 v[8:11], v144, s[4:5] offset:32
	global_load_dwordx4 v[12:15], v144, s[4:5] offset:48
	global_load_dword v16, v176, s[0:1]
	s_add_u32 s0, s0, 0x10000
	s_addc_u32 s1, s1, 0
	global_load_dword v17, v176, s[0:1]
	s_add_u32 s0, s0, 0x10000
	s_addc_u32 s1, s1, 0
	global_load_dword v18, v176, s[0:1]
	s_add_u32 s0, s0, 0x10000
	s_addc_u32 s1, s1, 0
	global_load_dword v19, v176, s[0:1]
	s_add_u32 s0, s0, 0x10000
	s_addc_u32 s1, s1, 0
	global_load_dword v20, v176, s[0:1]
	s_add_u32 s0, s0, 0x10000
	s_addc_u32 s1, s1, 0
	global_load_dword v21, v176, s[0:1]
	s_add_u32 s0, s0, 0x10000
	s_addc_u32 s1, s1, 0
	global_load_dword v22, v176, s[0:1]
	s_add_u32 s0, s0, 0x10000
	s_addc_u32 s1, s1, 0
	global_load_dword v23, v176, s[0:1]
	s_add_u32 s0, s0, 0x10000
	s_addc_u32 s1, s1, 0
	global_load_dword v24, v176, s[0:1]
	s_add_u32 s0, s0, 0x10000
	s_addc_u32 s1, s1, 0
	global_load_dword v25, v176, s[0:1]
	s_add_u32 s0, s0, 0x10000
	s_addc_u32 s1, s1, 0
	global_load_dword v26, v176, s[0:1]
	s_add_u32 s0, s0, 0x10000
	s_addc_u32 s1, s1, 0
	global_load_dword v27, v176, s[0:1]
	s_add_u32 s0, s0, 0x10000
	s_addc_u32 s1, s1, 0
	global_load_dword v28, v176, s[0:1]
	s_add_u32 s0, s0, 0x10000
	s_addc_u32 s1, s1, 0
	global_load_dword v29, v176, s[0:1]
	s_add_u32 s0, s0, 0x10000
	s_addc_u32 s1, s1, 0
	global_load_dword v30, v176, s[0:1]
	s_add_u32 s0, s0, 0x10000
	s_addc_u32 s1, s1, 0
	global_load_dword v31, v176, s[0:1]
	s_add_u32 s0, s0, 0x10000
	s_addc_u32 s1, s1, 0
	global_load_dwordx4 v[62:65], v144, s[4:5] offset:64
	global_load_dwordx4 v[66:69], v144, s[4:5] offset:80
	global_load_dwordx4 v[70:73], v144, s[4:5] offset:96
	global_load_dwordx4 v[128:131], v144, s[4:5] offset:112
	global_load_dword v132, v176, s[0:1]
	s_add_u32 s0, s0, 0x10000
	s_addc_u32 s1, s1, 0
	global_load_dword v133, v176, s[0:1]
	s_add_u32 s0, s0, 0x10000
	s_addc_u32 s1, s1, 0
	global_load_dword v134, v176, s[0:1]
	s_add_u32 s0, s0, 0x10000
	s_addc_u32 s1, s1, 0
	global_load_dword v135, v176, s[0:1]
	s_add_u32 s0, s0, 0x10000
	s_addc_u32 s1, s1, 0
	global_load_dword v136, v176, s[0:1]
	s_add_u32 s0, s0, 0x10000
	s_addc_u32 s1, s1, 0
	global_load_dword v137, v176, s[0:1]
	s_add_u32 s0, s0, 0x10000
	s_addc_u32 s1, s1, 0
	global_load_dword v138, v176, s[0:1]
	s_add_u32 s0, s0, 0x10000
	s_addc_u32 s1, s1, 0
	global_load_dword v139, v176, s[0:1]
	s_add_u32 s0, s0, 0x10000
	s_addc_u32 s1, s1, 0
	global_load_dword v91, v176, s[0:1]
	s_add_u32 s0, s0, 0x10000
	s_addc_u32 s1, s1, 0
	global_load_dword v92, v176, s[0:1]
	s_add_u32 s0, s0, 0x10000
	s_addc_u32 s1, s1, 0
	global_load_dword v93, v176, s[0:1]
	s_add_u32 s0, s0, 0x10000
	s_addc_u32 s1, s1, 0
	global_load_dword v94, v176, s[0:1]
	s_add_u32 s0, s0, 0x10000
	s_addc_u32 s1, s1, 0
	global_load_dword v95, v176, s[0:1]
	s_add_u32 s0, s0, 0x10000
	s_addc_u32 s1, s1, 0
	global_load_dword v74, v176, s[0:1]
	s_add_u32 s0, s0, 0x10000
	s_addc_u32 s1, s1, 0
	global_load_dword v75, v176, s[0:1]
	s_add_u32 s0, s0, 0x10000
	s_addc_u32 s1, s1, 0
	global_load_dword v170, v176, s[0:1]
	s_add_u32 s0, s0, 0x10000
	s_addc_u32 s1, s1, 0
	s_waitcnt vmcnt(20)
	v_mul_f32_e32 v0, 0x3fb8aa3b, v0
	v_mul_f32_e32 v1, 0x3fb8aa3b, v1
	v_mul_f32_e32 v2, 0x3fb8aa3b, v2
	v_mul_f32_e32 v3, 0x3fb8aa3b, v3
	v_mul_f32_e32 v4, 0x3fb8aa3b, v4
	v_mul_f32_e32 v5, 0x3fb8aa3b, v5
	v_mul_f32_e32 v6, 0x3fb8aa3b, v6
	v_mul_f32_e32 v7, 0x3fb8aa3b, v7
	v_mul_f32_e32 v8, 0x3fb8aa3b, v8
	v_mul_f32_e32 v9, 0x3fb8aa3b, v9
	v_mul_f32_e32 v10, 0x3fb8aa3b, v10
	v_mul_f32_e32 v11, 0x3fb8aa3b, v11
	v_mul_f32_e32 v12, 0x3fb8aa3b, v12
	v_mul_f32_e32 v13, 0x3fb8aa3b, v13
	v_mul_f32_e32 v14, 0x3fb8aa3b, v14
	v_mul_f32_e32 v15, 0x3fb8aa3b, v15
	v_exp_f32_e32 v0, v0
	v_exp_f32_e32 v1, v1
	v_exp_f32_e32 v2, v2
	v_exp_f32_e32 v3, v3
	v_exp_f32_e32 v4, v4
	v_exp_f32_e32 v5, v5
	v_exp_f32_e32 v6, v6
	v_exp_f32_e32 v7, v7
	v_exp_f32_e32 v8, v8
	v_exp_f32_e32 v9, v9
	v_exp_f32_e32 v10, v10
	v_exp_f32_e32 v11, v11
	v_exp_f32_e32 v12, v12
	v_exp_f32_e32 v13, v13
	v_exp_f32_e32 v14, v14
	v_exp_f32_e32 v15, v15
	s_nop 0
	v_fmac_f32_e32 v16, 0, v0
	v_cvt_pk_bf16_f32 v181, v16, v16
	global_store_short v180, v181, s[2:3]
	s_add_u32 s2, s2, 0x8000
	s_addc_u32 s3, s3, 0
	v_fmac_f32_e32 v17, v16, v1
	v_cvt_pk_bf16_f32 v181, v17, v17
	global_store_short v180, v181, s[2:3]
	s_add_u32 s2, s2, 0x8000
	s_addc_u32 s3, s3, 0
	v_fmac_f32_e32 v18, v17, v2
	v_cvt_pk_bf16_f32 v181, v18, v18
	global_store_short v180, v181, s[2:3]
	s_add_u32 s2, s2, 0x8000
	s_addc_u32 s3, s3, 0
	v_fmac_f32_e32 v19, v18, v3
	v_cvt_pk_bf16_f32 v181, v19, v19
	global_store_short v180, v181, s[2:3]
	s_add_u32 s2, s2, 0x8000
	s_addc_u32 s3, s3, 0
	v_fmac_f32_e32 v20, v19, v4
	v_cvt_pk_bf16_f32 v181, v20, v20
	global_store_short v180, v181, s[2:3]
	s_add_u32 s2, s2, 0x8000
	s_addc_u32 s3, s3, 0
	v_fmac_f32_e32 v21, v20, v5
	v_cvt_pk_bf16_f32 v181, v21, v21
	global_store_short v180, v181, s[2:3]
	s_add_u32 s2, s2, 0x8000
	s_addc_u32 s3, s3, 0
	v_fmac_f32_e32 v22, v21, v6
	v_cvt_pk_bf16_f32 v181, v22, v22
	global_store_short v180, v181, s[2:3]
	s_add_u32 s2, s2, 0x8000
	s_addc_u32 s3, s3, 0
	v_fmac_f32_e32 v23, v22, v7
	v_cvt_pk_bf16_f32 v181, v23, v23
	global_store_short v180, v181, s[2:3]
	s_add_u32 s2, s2, 0x8000
	s_addc_u32 s3, s3, 0
	v_fmac_f32_e32 v24, v23, v8
	v_cvt_pk_bf16_f32 v181, v24, v24
	global_store_short v180, v181, s[2:3]
	s_add_u32 s2, s2, 0x8000
	s_addc_u32 s3, s3, 0
	v_fmac_f32_e32 v25, v24, v9
	v_cvt_pk_bf16_f32 v181, v25, v25
	global_store_short v180, v181, s[2:3]
	s_add_u32 s2, s2, 0x8000
	s_addc_u32 s3, s3, 0
	v_fmac_f32_e32 v26, v25, v10
	v_cvt_pk_bf16_f32 v181, v26, v26
	global_store_short v180, v181, s[2:3]
	s_add_u32 s2, s2, 0x8000
	s_addc_u32 s3, s3, 0
	v_fmac_f32_e32 v27, v26, v11
	v_cvt_pk_bf16_f32 v181, v27, v27
	global_store_short v180, v181, s[2:3]
	s_add_u32 s2, s2, 0x8000
	s_addc_u32 s3, s3, 0
	v_fmac_f32_e32 v28, v27, v12
	v_cvt_pk_bf16_f32 v181, v28, v28
	global_store_short v180, v181, s[2:3]
	s_add_u32 s2, s2, 0x8000
	s_addc_u32 s3, s3, 0
	v_fmac_f32_e32 v29, v28, v13
	v_cvt_pk_bf16_f32 v181, v29, v29
	global_store_short v180, v181, s[2:3]
	s_add_u32 s2, s2, 0x8000
	s_addc_u32 s3, s3, 0
	v_fmac_f32_e32 v30, v29, v14
	v_cvt_pk_bf16_f32 v181, v30, v30
	global_store_short v180, v181, s[2:3]
	s_add_u32 s2, s2, 0x8000
	s_addc_u32 s3, s3, 0
	v_fmac_f32_e32 v31, v30, v15
	v_cvt_pk_bf16_f32 v181, v31, v31
	global_store_short v180, v181, s[2:3]
	s_add_u32 s2, s2, 0x8000
	s_addc_u32 s3, s3, 0
	v_mov_b32_e32 v171, v31
	global_load_dwordx4 v[0:3], v144, s[4:5] offset:128
	global_load_dwordx4 v[4:7], v144, s[4:5] offset:144
	global_load_dwordx4 v[8:11], v144, s[4:5] offset:160
	global_load_dwordx4 v[12:15], v144, s[4:5] offset:176
	global_load_dword v16, v176, s[0:1]
	s_add_u32 s0, s0, 0x10000
	s_addc_u32 s1, s1, 0
	global_load_dword v17, v176, s[0:1]
	s_add_u32 s0, s0, 0x10000
	s_addc_u32 s1, s1, 0
	global_load_dword v18, v176, s[0:1]
	s_add_u32 s0, s0, 0x10000
	s_addc_u32 s1, s1, 0
	global_load_dword v19, v176, s[0:1]
	s_add_u32 s0, s0, 0x10000
	s_addc_u32 s1, s1, 0
	global_load_dword v20, v176, s[0:1]
	s_add_u32 s0, s0, 0x10000
	s_addc_u32 s1, s1, 0
	global_load_dword v21, v176, s[0:1]
	s_add_u32 s0, s0, 0x10000
	s_addc_u32 s1, s1, 0
	global_load_dword v22, v176, s[0:1]
	s_add_u32 s0, s0, 0x10000
	s_addc_u32 s1, s1, 0
	global_load_dword v23, v176, s[0:1]
	s_add_u32 s0, s0, 0x10000
	s_addc_u32 s1, s1, 0
	global_load_dword v24, v176, s[0:1]
	s_add_u32 s0, s0, 0x10000
	s_addc_u32 s1, s1, 0
	global_load_dword v25, v176, s[0:1]
	s_add_u32 s0, s0, 0x10000
	s_addc_u32 s1, s1, 0
	global_load_dword v26, v176, s[0:1]
	s_add_u32 s0, s0, 0x10000
	s_addc_u32 s1, s1, 0
	global_load_dword v27, v176, s[0:1]
	s_add_u32 s0, s0, 0x10000
	s_addc_u32 s1, s1, 0
	global_load_dword v28, v176, s[0:1]
	s_add_u32 s0, s0, 0x10000
	s_addc_u32 s1, s1, 0
	global_load_dword v29, v176, s[0:1]
	s_add_u32 s0, s0, 0x10000
	s_addc_u32 s1, s1, 0
	global_load_dword v30, v176, s[0:1]
	s_add_u32 s0, s0, 0x10000
	s_addc_u32 s1, s1, 0
	global_load_dword v31, v176, s[0:1]
	s_add_u32 s0, s0, 0x10000
	s_addc_u32 s1, s1, 0
	s_waitcnt vmcnt(36)
	v_mul_f32_e32 v62, 0x3fb8aa3b, v62
	v_mul_f32_e32 v63, 0x3fb8aa3b, v63
	v_mul_f32_e32 v64, 0x3fb8aa3b, v64
	v_mul_f32_e32 v65, 0x3fb8aa3b, v65
	v_mul_f32_e32 v66, 0x3fb8aa3b, v66
	v_mul_f32_e32 v67, 0x3fb8aa3b, v67
	v_mul_f32_e32 v68, 0x3fb8aa3b, v68
	v_mul_f32_e32 v69, 0x3fb8aa3b, v69
	v_mul_f32_e32 v70, 0x3fb8aa3b, v70
	v_mul_f32_e32 v71, 0x3fb8aa3b, v71
	v_mul_f32_e32 v72, 0x3fb8aa3b, v72
	v_mul_f32_e32 v73, 0x3fb8aa3b, v73
	v_mul_f32_e32 v128, 0x3fb8aa3b, v128
	v_mul_f32_e32 v129, 0x3fb8aa3b, v129
	v_mul_f32_e32 v130, 0x3fb8aa3b, v130
	v_mul_f32_e32 v131, 0x3fb8aa3b, v131
	v_exp_f32_e32 v62, v62
	v_exp_f32_e32 v63, v63
	v_exp_f32_e32 v64, v64
	v_exp_f32_e32 v65, v65
	v_exp_f32_e32 v66, v66
	v_exp_f32_e32 v67, v67
	v_exp_f32_e32 v68, v68
	v_exp_f32_e32 v69, v69
	v_exp_f32_e32 v70, v70
	v_exp_f32_e32 v71, v71
	v_exp_f32_e32 v72, v72
	v_exp_f32_e32 v73, v73
	v_exp_f32_e32 v128, v128
	v_exp_f32_e32 v129, v129
	v_exp_f32_e32 v130, v130
	v_exp_f32_e32 v131, v131
	s_nop 0
	v_fmac_f32_e32 v132, v171, v62
	v_cvt_pk_bf16_f32 v181, v132, v132
	global_store_short v180, v181, s[2:3]
	s_add_u32 s2, s2, 0x8000
	s_addc_u32 s3, s3, 0
	v_fmac_f32_e32 v133, v132, v63
	v_cvt_pk_bf16_f32 v181, v133, v133
	global_store_short v180, v181, s[2:3]
	s_add_u32 s2, s2, 0x8000
	s_addc_u32 s3, s3, 0
	v_fmac_f32_e32 v134, v133, v64
	v_cvt_pk_bf16_f32 v181, v134, v134
	global_store_short v180, v181, s[2:3]
	s_add_u32 s2, s2, 0x8000
	s_addc_u32 s3, s3, 0
	v_fmac_f32_e32 v135, v134, v65
	v_cvt_pk_bf16_f32 v181, v135, v135
	global_store_short v180, v181, s[2:3]
	s_add_u32 s2, s2, 0x8000
	s_addc_u32 s3, s3, 0
	v_fmac_f32_e32 v136, v135, v66
	v_cvt_pk_bf16_f32 v181, v136, v136
	global_store_short v180, v181, s[2:3]
	s_add_u32 s2, s2, 0x8000
	s_addc_u32 s3, s3, 0
	v_fmac_f32_e32 v137, v136, v67
	v_cvt_pk_bf16_f32 v181, v137, v137
	global_store_short v180, v181, s[2:3]
	s_add_u32 s2, s2, 0x8000
	s_addc_u32 s3, s3, 0
	v_fmac_f32_e32 v138, v137, v68
	v_cvt_pk_bf16_f32 v181, v138, v138
	global_store_short v180, v181, s[2:3]
	s_add_u32 s2, s2, 0x8000
	s_addc_u32 s3, s3, 0
	v_fmac_f32_e32 v139, v138, v69
	v_cvt_pk_bf16_f32 v181, v139, v139
	global_store_short v180, v181, s[2:3]
	s_add_u32 s2, s2, 0x8000
	s_addc_u32 s3, s3, 0
	v_fmac_f32_e32 v91, v139, v70
	v_cvt_pk_bf16_f32 v181, v91, v91
	global_store_short v180, v181, s[2:3]
	s_add_u32 s2, s2, 0x8000
	s_addc_u32 s3, s3, 0
	v_fmac_f32_e32 v92, v91, v71
	v_cvt_pk_bf16_f32 v181, v92, v92
	global_store_short v180, v181, s[2:3]
	s_add_u32 s2, s2, 0x8000
	s_addc_u32 s3, s3, 0
	v_fmac_f32_e32 v93, v92, v72
	v_cvt_pk_bf16_f32 v181, v93, v93
	global_store_short v180, v181, s[2:3]
	s_add_u32 s2, s2, 0x8000
	s_addc_u32 s3, s3, 0
	v_fmac_f32_e32 v94, v93, v73
	v_cvt_pk_bf16_f32 v181, v94, v94
	global_store_short v180, v181, s[2:3]
	s_add_u32 s2, s2, 0x8000
	s_addc_u32 s3, s3, 0
	v_fmac_f32_e32 v95, v94, v128
	v_cvt_pk_bf16_f32 v181, v95, v95
	global_store_short v180, v181, s[2:3]
	s_add_u32 s2, s2, 0x8000
	s_addc_u32 s3, s3, 0
	v_fmac_f32_e32 v74, v95, v129
	v_cvt_pk_bf16_f32 v181, v74, v74
	global_store_short v180, v181, s[2:3]
	s_add_u32 s2, s2, 0x8000
	s_addc_u32 s3, s3, 0
	v_fmac_f32_e32 v75, v74, v130
	v_cvt_pk_bf16_f32 v181, v75, v75
	global_store_short v180, v181, s[2:3]
	s_add_u32 s2, s2, 0x8000
	s_addc_u32 s3, s3, 0
	v_fmac_f32_e32 v170, v75, v131
	v_cvt_pk_bf16_f32 v181, v170, v170
	global_store_short v180, v181, s[2:3]
	s_add_u32 s2, s2, 0x8000
	s_addc_u32 s3, s3, 0
	v_mov_b32_e32 v171, v170
	global_load_dwordx4 v[62:65], v144, s[4:5] offset:192
	global_load_dwordx4 v[66:69], v144, s[4:5] offset:208
	global_load_dwordx4 v[70:73], v144, s[4:5] offset:224
	global_load_dwordx3 v[128:130], v144, s[4:5] offset:240
	global_load_dword v132, v176, s[0:1]
	s_add_u32 s0, s0, 0x10000
	s_addc_u32 s1, s1, 0
	global_load_dword v133, v176, s[0:1]
	s_add_u32 s0, s0, 0x10000
	s_addc_u32 s1, s1, 0
	global_load_dword v134, v176, s[0:1]
	s_add_u32 s0, s0, 0x10000
	s_addc_u32 s1, s1, 0
	global_load_dword v135, v176, s[0:1]
	s_add_u32 s0, s0, 0x10000
	s_addc_u32 s1, s1, 0
	global_load_dword v136, v176, s[0:1]
	s_add_u32 s0, s0, 0x10000
	s_addc_u32 s1, s1, 0
	global_load_dword v137, v176, s[0:1]
	s_add_u32 s0, s0, 0x10000
	s_addc_u32 s1, s1, 0
	global_load_dword v138, v176, s[0:1]
	s_add_u32 s0, s0, 0x10000
	s_addc_u32 s1, s1, 0
	global_load_dword v139, v176, s[0:1]
	s_add_u32 s0, s0, 0x10000
	s_addc_u32 s1, s1, 0
	global_load_dword v91, v176, s[0:1]
	s_add_u32 s0, s0, 0x10000
	s_addc_u32 s1, s1, 0
	global_load_dword v92, v176, s[0:1]
	s_add_u32 s0, s0, 0x10000
	s_addc_u32 s1, s1, 0
	global_load_dword v93, v176, s[0:1]
	s_add_u32 s0, s0, 0x10000
	s_addc_u32 s1, s1, 0
	global_load_dword v94, v176, s[0:1]
	s_add_u32 s0, s0, 0x10000
	s_addc_u32 s1, s1, 0
	global_load_dword v95, v176, s[0:1]
	s_add_u32 s0, s0, 0x10000
	s_addc_u32 s1, s1, 0
	global_load_dword v74, v176, s[0:1]
	s_add_u32 s0, s0, 0x10000
	s_addc_u32 s1, s1, 0
	global_load_dword v75, v176, s[0:1]
	s_add_u32 s0, s0, 0x10000
	s_addc_u32 s1, s1, 0
	s_waitcnt vmcnt(35)
	v_mul_f32_e32 v0, 0x3fb8aa3b, v0
	v_mul_f32_e32 v1, 0x3fb8aa3b, v1
	v_mul_f32_e32 v2, 0x3fb8aa3b, v2
	v_mul_f32_e32 v3, 0x3fb8aa3b, v3
	v_mul_f32_e32 v4, 0x3fb8aa3b, v4
	v_mul_f32_e32 v5, 0x3fb8aa3b, v5
	v_mul_f32_e32 v6, 0x3fb8aa3b, v6
	v_mul_f32_e32 v7, 0x3fb8aa3b, v7
	v_mul_f32_e32 v8, 0x3fb8aa3b, v8
	v_mul_f32_e32 v9, 0x3fb8aa3b, v9
	v_mul_f32_e32 v10, 0x3fb8aa3b, v10
	v_mul_f32_e32 v11, 0x3fb8aa3b, v11
	v_mul_f32_e32 v12, 0x3fb8aa3b, v12
	v_mul_f32_e32 v13, 0x3fb8aa3b, v13
	v_mul_f32_e32 v14, 0x3fb8aa3b, v14
	v_mul_f32_e32 v15, 0x3fb8aa3b, v15
	v_exp_f32_e32 v0, v0
	v_exp_f32_e32 v1, v1
	v_exp_f32_e32 v2, v2
	v_exp_f32_e32 v3, v3
	v_exp_f32_e32 v4, v4
	v_exp_f32_e32 v5, v5
	v_exp_f32_e32 v6, v6
	v_exp_f32_e32 v7, v7
	v_exp_f32_e32 v8, v8
	v_exp_f32_e32 v9, v9
	v_exp_f32_e32 v10, v10
	v_exp_f32_e32 v11, v11
	v_exp_f32_e32 v12, v12
	v_exp_f32_e32 v13, v13
	v_exp_f32_e32 v14, v14
	v_exp_f32_e32 v15, v15
	s_nop 0
	v_fmac_f32_e32 v16, v171, v0
	v_cvt_pk_bf16_f32 v181, v16, v16
	global_store_short v180, v181, s[2:3]
	s_add_u32 s2, s2, 0x8000
	s_addc_u32 s3, s3, 0
	v_fmac_f32_e32 v17, v16, v1
	v_cvt_pk_bf16_f32 v181, v17, v17
	global_store_short v180, v181, s[2:3]
	s_add_u32 s2, s2, 0x8000
	s_addc_u32 s3, s3, 0
	v_fmac_f32_e32 v18, v17, v2
	v_cvt_pk_bf16_f32 v181, v18, v18
	global_store_short v180, v181, s[2:3]
	s_add_u32 s2, s2, 0x8000
	s_addc_u32 s3, s3, 0
	v_fmac_f32_e32 v19, v18, v3
	v_cvt_pk_bf16_f32 v181, v19, v19
	global_store_short v180, v181, s[2:3]
	s_add_u32 s2, s2, 0x8000
	s_addc_u32 s3, s3, 0
	v_fmac_f32_e32 v20, v19, v4
	v_cvt_pk_bf16_f32 v181, v20, v20
	global_store_short v180, v181, s[2:3]
	s_add_u32 s2, s2, 0x8000
	s_addc_u32 s3, s3, 0
	v_fmac_f32_e32 v21, v20, v5
	v_cvt_pk_bf16_f32 v181, v21, v21
	global_store_short v180, v181, s[2:3]
	s_add_u32 s2, s2, 0x8000
	s_addc_u32 s3, s3, 0
	v_fmac_f32_e32 v22, v21, v6
	v_cvt_pk_bf16_f32 v181, v22, v22
	global_store_short v180, v181, s[2:3]
	s_add_u32 s2, s2, 0x8000
	s_addc_u32 s3, s3, 0
	v_fmac_f32_e32 v23, v22, v7
	v_cvt_pk_bf16_f32 v181, v23, v23
	global_store_short v180, v181, s[2:3]
	s_add_u32 s2, s2, 0x8000
	s_addc_u32 s3, s3, 0
	v_fmac_f32_e32 v24, v23, v8
	v_cvt_pk_bf16_f32 v181, v24, v24
	global_store_short v180, v181, s[2:3]
	s_add_u32 s2, s2, 0x8000
	s_addc_u32 s3, s3, 0
	v_fmac_f32_e32 v25, v24, v9
	v_cvt_pk_bf16_f32 v181, v25, v25
	global_store_short v180, v181, s[2:3]
	s_add_u32 s2, s2, 0x8000
	s_addc_u32 s3, s3, 0
	v_fmac_f32_e32 v26, v25, v10
	v_cvt_pk_bf16_f32 v181, v26, v26
	global_store_short v180, v181, s[2:3]
	s_add_u32 s2, s2, 0x8000
	s_addc_u32 s3, s3, 0
	v_fmac_f32_e32 v27, v26, v11
	v_cvt_pk_bf16_f32 v181, v27, v27
	global_store_short v180, v181, s[2:3]
	s_add_u32 s2, s2, 0x8000
	s_addc_u32 s3, s3, 0
	v_fmac_f32_e32 v28, v27, v12
	v_cvt_pk_bf16_f32 v181, v28, v28
	global_store_short v180, v181, s[2:3]
	s_add_u32 s2, s2, 0x8000
	s_addc_u32 s3, s3, 0
	v_fmac_f32_e32 v29, v28, v13
	v_cvt_pk_bf16_f32 v181, v29, v29
	global_store_short v180, v181, s[2:3]
	s_add_u32 s2, s2, 0x8000
	s_addc_u32 s3, s3, 0
	v_fmac_f32_e32 v30, v29, v14
	v_cvt_pk_bf16_f32 v181, v30, v30
	global_store_short v180, v181, s[2:3]
	s_add_u32 s2, s2, 0x8000
	s_addc_u32 s3, s3, 0
	v_fmac_f32_e32 v31, v30, v15
	v_cvt_pk_bf16_f32 v181, v31, v31
	global_store_short v180, v181, s[2:3]
	s_add_u32 s2, s2, 0x8000
	s_addc_u32 s3, s3, 0
	v_mov_b32_e32 v171, v31
	s_waitcnt vmcnt(16)
	v_mul_f32_e32 v62, 0x3fb8aa3b, v62
	v_mul_f32_e32 v63, 0x3fb8aa3b, v63
	v_mul_f32_e32 v64, 0x3fb8aa3b, v64
	v_mul_f32_e32 v65, 0x3fb8aa3b, v65
	v_mul_f32_e32 v66, 0x3fb8aa3b, v66
	v_mul_f32_e32 v67, 0x3fb8aa3b, v67
	v_mul_f32_e32 v68, 0x3fb8aa3b, v68
	v_mul_f32_e32 v69, 0x3fb8aa3b, v69
	v_mul_f32_e32 v70, 0x3fb8aa3b, v70
	v_mul_f32_e32 v71, 0x3fb8aa3b, v71
	v_mul_f32_e32 v72, 0x3fb8aa3b, v72
	v_mul_f32_e32 v73, 0x3fb8aa3b, v73
	v_mul_f32_e32 v128, 0x3fb8aa3b, v128
	v_mul_f32_e32 v129, 0x3fb8aa3b, v129
	v_mul_f32_e32 v130, 0x3fb8aa3b, v130
	v_exp_f32_e32 v62, v62
	v_exp_f32_e32 v63, v63
	v_exp_f32_e32 v64, v64
	v_exp_f32_e32 v65, v65
	v_exp_f32_e32 v66, v66
	v_exp_f32_e32 v67, v67
	v_exp_f32_e32 v68, v68
	v_exp_f32_e32 v69, v69
	v_exp_f32_e32 v70, v70
	v_exp_f32_e32 v71, v71
	v_exp_f32_e32 v72, v72
	v_exp_f32_e32 v73, v73
	v_exp_f32_e32 v128, v128
	v_exp_f32_e32 v129, v129
	v_exp_f32_e32 v130, v130
	s_nop 0
	v_fmac_f32_e32 v132, v171, v62
	v_cvt_pk_bf16_f32 v181, v132, v132
	global_store_short v180, v181, s[2:3]
	s_add_u32 s2, s2, 0x8000
	s_addc_u32 s3, s3, 0
	v_fmac_f32_e32 v133, v132, v63
	v_cvt_pk_bf16_f32 v181, v133, v133
	global_store_short v180, v181, s[2:3]
	s_add_u32 s2, s2, 0x8000
	s_addc_u32 s3, s3, 0
	v_fmac_f32_e32 v134, v133, v64
	v_cvt_pk_bf16_f32 v181, v134, v134
	global_store_short v180, v181, s[2:3]
	s_add_u32 s2, s2, 0x8000
	s_addc_u32 s3, s3, 0
	v_fmac_f32_e32 v135, v134, v65
	v_cvt_pk_bf16_f32 v181, v135, v135
	global_store_short v180, v181, s[2:3]
	s_add_u32 s2, s2, 0x8000
	s_addc_u32 s3, s3, 0
	v_fmac_f32_e32 v136, v135, v66
	v_cvt_pk_bf16_f32 v181, v136, v136
	global_store_short v180, v181, s[2:3]
	s_add_u32 s2, s2, 0x8000
	s_addc_u32 s3, s3, 0
	v_fmac_f32_e32 v137, v136, v67
	v_cvt_pk_bf16_f32 v181, v137, v137
	global_store_short v180, v181, s[2:3]
	s_add_u32 s2, s2, 0x8000
	s_addc_u32 s3, s3, 0
	v_fmac_f32_e32 v138, v137, v68
	v_cvt_pk_bf16_f32 v181, v138, v138
	global_store_short v180, v181, s[2:3]
	s_add_u32 s2, s2, 0x8000
	s_addc_u32 s3, s3, 0
	v_fmac_f32_e32 v139, v138, v69
	v_cvt_pk_bf16_f32 v181, v139, v139
	global_store_short v180, v181, s[2:3]
	s_add_u32 s2, s2, 0x8000
	s_addc_u32 s3, s3, 0
	v_fmac_f32_e32 v91, v139, v70
	v_cvt_pk_bf16_f32 v181, v91, v91
	global_store_short v180, v181, s[2:3]
	s_add_u32 s2, s2, 0x8000
	s_addc_u32 s3, s3, 0
	v_fmac_f32_e32 v92, v91, v71
	v_cvt_pk_bf16_f32 v181, v92, v92
	global_store_short v180, v181, s[2:3]
	s_add_u32 s2, s2, 0x8000
	s_addc_u32 s3, s3, 0
	v_fmac_f32_e32 v93, v92, v72
	v_cvt_pk_bf16_f32 v181, v93, v93
	global_store_short v180, v181, s[2:3]
	s_add_u32 s2, s2, 0x8000
	s_addc_u32 s3, s3, 0
	v_fmac_f32_e32 v94, v93, v73
	v_cvt_pk_bf16_f32 v181, v94, v94
	global_store_short v180, v181, s[2:3]
	s_add_u32 s2, s2, 0x8000
	s_addc_u32 s3, s3, 0
	v_fmac_f32_e32 v95, v94, v128
	v_cvt_pk_bf16_f32 v181, v95, v95
	global_store_short v180, v181, s[2:3]
	s_add_u32 s2, s2, 0x8000
	s_addc_u32 s3, s3, 0
	v_fmac_f32_e32 v74, v95, v129
	v_cvt_pk_bf16_f32 v181, v74, v74
	global_store_short v180, v181, s[2:3]
	s_add_u32 s2, s2, 0x8000
	s_addc_u32 s3, s3, 0
	v_fmac_f32_e32 v75, v74, v130
	v_cvt_pk_bf16_f32 v181, v75, v75
	global_store_short v180, v181, s[2:3]
	s_add_u32 s2, s2, 0x8000
	s_addc_u32 s3, s3, 0
	v_mov_b32_e32 v171, v75
